# FFN down GEMM residual epilogue: the 32 read-modify-write X loads (each pair waited with vmcnt(0) right behind the previous group's stores) now run 7 groups ahead in spare registers with counted waits
# speedup vs baseline: 1.0106x; 1.0018x over previous
; __device__ __forceinline__ void store8bf(bf16_t* p, f32x4 a, f32x4 b) { u32x4 w; w.x = pk2(a[0], a[1]); w.y = pk2(a[2], a[3]); w.z = pk2(b[0], b[1]); w.w = pk2(b[2], b[3]); *(u32x4*)p = w; }
; __device__ __forceinline__ float sigmoid_f(float v) { return 1.0f / (1.0f + __expf(-v)); }
;     __device__ __forceinline__ void operator()(const f32x4 (&acc)[2][2][4][2], const pg8::Unit& u, int wr, int wc, int fr, int fq) const {
;     ...
;         const int rowb = u.pm * 256 + wr * 64 + fr, colb = u.pn * (GLU ? 128 : 256) + wc * 32 + 8 * fq;
; #pragma unroll
;         for (int ai = 0; ai < 2; ++ai)
; #pragma unroll
;             for (int m = 0; m < 4; ++m) {
;                 const int t = rowb + ai * 128 + m * 16; float ss = 0.f;
;                 float* xr = X + (size_t)t * D + colb; bf16_t* xbr = XB + (size_t)t * D + colb;
;                 if (GLU) {
;                     f32x4 y0, y1;
; #pragma unroll
;                     for (int jj = 0; jj < 4; ++jj) { y0[jj] = acc[ai][0][m][0][jj] * sigmoid_f(acc[ai][1][m][0][jj]); y1[jj] = acc[ai][0][m][1][jj] * sigmoid_f(acc[ai][1][m][1][jj]); }
;                     const f32x4 x0 = *(const f32x4*)xr + y0, x1 = *(const f32x4*)(xr + 4) + y1;
;                     if (!dry) { *(f32x4*)xr = x0; *(f32x4*)(xr + 4) = x1; store8bf(xbr, x0, x1); }
;                     ss += (x0[0] * x0[0] + x0[1] * x0[1]) + (x0[2] * x0[2] + x0[3] * x0[3]) + (x1[0] * x1[0] + x1[1] * x1[1]) + (x1[2] * x1[2] + x1[3] * x1[3]);
;                 } else {
; #pragma unroll
;                     for (int bj = 0; bj < 2; ++bj) {
;                         const f32x4 x0 = *(const f32x4*)(xr + bj * 128) + acc[ai][bj][m][0], x1 = *(const f32x4*)(xr + bj * 128 + 4) + acc[ai][bj][m][1];
;                         if (!dry) { *(f32x4*)(xr + bj * 128) = x0; *(f32x4*)(xr + bj * 128 + 4) = x1; store8bf(xbr + bj * 128, x0, x1); }
;                         ss += (x0[0] * x0[0] + x0[1] * x0[1]) + (x0[2] * x0[2] + x0[3] * x0[3]) + (x1[0] * x1[0] + x1[1] * x1[1]) + (x1[2] * x1[2] + x1[3] * x1[3]);
;                     }
;                 }
;                 ss += __shfl_xor(ss, 16); ss += __shfl_xor(ss, 32);
;                 if (fq == 0 && !dry) rsp_next[(size_t)t * 64 + u.pn * 4 + wc] = ss;
;             }
.LBB0_1311:
	v_ashrrev_i32_e32 v139, 31, v138
	v_and_b32_e32 v145, 64, v229
	v_lshl_add_u64 v[142:143], v[138:139], 2, s[26:27]
	v_lshl_add_u64 v[140:141], v[138:139], 1, s[24:25]
	v_xor_b32_e32 v139, 16, v229
	v_add_u32_e32 v145, 64, v145
	v_cmp_lt_i32_e32 vcc, v139, v145
	v_lshl_add_u32 v144, s8, 8, v148
	s_nop 0
	v_cndmask_b32_e32 v139, v229, v139, vcc
	v_lshlrev_b32_e32 v153, 2, v139
	v_xor_b32_e32 v139, 32, v229
	v_cmp_lt_i32_e32 vcc, v139, v145
	v_ashrrev_i32_e32 v145, 31, v144
	v_lshlrev_b64 v[146:147], 13, v[144:145]
	v_lshl_add_u64 v[146:147], v[142:143], 0, v[146:147]
	v_lshlrev_b64 v[154:155], 12, v[144:145]
	v_lshl_add_u64 v[166:167], v[140:141], 0, v[154:155]
	v_mov_b64_e32 v[216:217], v[146:147]
	s_mov_b32 s101, 0
	global_load_dwordx4 v[170:173], v[216:217], off offset:16
	global_load_dwordx4 v[174:177], v[216:217], off
	s_mov_b32 s100, 0x200
	v_lshl_add_u64 v[190:191], v[216:217], 0, s[100:101]
	global_load_dwordx4 v[178:181], v[190:191], off offset:16
	global_load_dwordx4 v[182:185], v[190:191], off
	s_mov_b32 s100, 0x20000
	v_lshl_add_u64 v[190:191], v[216:217], 0, s[100:101]
	global_load_dwordx4 v[186:189], v[190:191], off offset:16
	global_load_dwordx4 v[196:199], v[190:191], off
	s_mov_b32 s100, 0x20200
	v_lshl_add_u64 v[190:191], v[216:217], 0, s[100:101]
	global_load_dwordx4 v[200:203], v[190:191], off offset:16
	global_load_dwordx4 v[204:207], v[190:191], off
	s_mov_b32 s100, 0x40000
	v_lshl_add_u64 v[190:191], v[216:217], 0, s[100:101]
	global_load_dwordx4 v[208:211], v[190:191], off offset:16
	global_load_dwordx4 v[212:215], v[190:191], off
	s_mov_b32 s100, 0x40200
	v_lshl_add_u64 v[190:191], v[216:217], 0, s[100:101]
	global_load_dwordx4 v[224:227], v[190:191], off offset:16
	global_load_dwordx4 v[236:239], v[190:191], off
	s_mov_b32 s100, 0x60000
	v_lshl_add_u64 v[190:191], v[216:217], 0, s[100:101]
	global_load_dwordx4 v[240:243], v[190:191], off offset:16
	global_load_dwordx4 v[244:247], v[190:191], off
	s_waitcnt vmcnt(12)
	v_mov_b64_e32 v[154:155], v[170:171]
	v_mov_b64_e32 v[156:157], v[172:173]
	v_mov_b64_e32 v[158:159], v[174:175]
	v_mov_b64_e32 v[160:161], v[176:177]
	v_cndmask_b32_e32 v139, v229, v139, vcc
	v_lshlrev_b32_e32 v139, 2, v139
	v_pk_add_f32 v[156:157], v[122:123], v[156:157]
	v_pk_add_f32 v[160:161], v[126:127], v[160:161]
	v_pk_add_f32 v[158:159], v[124:125], v[158:159]
	v_pk_add_f32 v[154:155], v[120:121], v[154:155]
	global_store_dwordx4 v[146:147], v[158:161], off
	global_store_dwordx4 v[146:147], v[154:157], off offset:16
	s_mov_b32 s100, 0x60200
	v_lshl_add_u64 v[190:191], v[216:217], 0, s[100:101]
	global_load_dwordx4 v[170:173], v[190:191], off offset:16
	global_load_dwordx4 v[174:177], v[190:191], off
	v_cvt_pk_bf16_f32 v162, v158, v159
	v_mul_f32_e32 v159, v159, v159
	v_fmac_f32_e32 v159, v158, v158
	v_mul_f32_e32 v158, v161, v161
	v_cvt_pk_bf16_f32 v164, v154, v155
	v_fmac_f32_e32 v158, v160, v160
	v_mul_f32_e32 v155, v155, v155
	v_add_f32_e32 v158, v159, v158
	v_fmac_f32_e32 v155, v154, v154
	v_cvt_pk_bf16_f32 v163, v160, v161
	v_cvt_pk_bf16_f32 v165, v156, v157
	v_add_f32_e32 v154, v158, v155
	v_mul_f32_e32 v155, v157, v157
	global_store_dwordx4 v[166:167], v[162:165], off
	v_fmac_f32_e32 v155, v156, v156
	v_add_f32_e32 v168, v155, v154
	s_waitcnt vmcnt(15)
	v_mov_b64_e32 v[154:155], v[178:179]
	v_mov_b64_e32 v[156:157], v[180:181]
	v_mov_b64_e32 v[158:159], v[182:183]
	v_mov_b64_e32 v[160:161], v[184:185]
	v_pk_add_f32 v[156:157], v[106:107], v[156:157]
	v_pk_add_f32 v[160:161], v[110:111], v[160:161]
	v_pk_add_f32 v[158:159], v[108:109], v[158:159]
	v_pk_add_f32 v[154:155], v[104:105], v[154:155]
	global_store_dwordx4 v[146:147], v[158:161], off offset:512
	global_store_dwordx4 v[146:147], v[154:157], off offset:528
	s_mov_b32 s100, 0x100000
	v_lshl_add_u64 v[190:191], v[216:217], 0, s[100:101]
	global_load_dwordx4 v[178:181], v[190:191], off offset:16
	global_load_dwordx4 v[182:185], v[190:191], off
	v_mul_f32_e32 v146, v159, v159
	v_mul_f32_e32 v147, v161, v161
	v_fmac_f32_e32 v146, v158, v158
	v_fmac_f32_e32 v147, v160, v160
	v_add_f32_e32 v146, v146, v147
	v_mul_f32_e32 v147, v155, v155
	v_fmac_f32_e32 v147, v154, v154
	v_add_f32_e32 v146, v146, v147
	v_mul_f32_e32 v147, v157, v157
	v_fmac_f32_e32 v147, v156, v156
	v_add_f32_e32 v146, v147, v146
	v_add_f32_e32 v146, v168, v146
	ds_bpermute_b32 v147, v153, v146
	v_cvt_pk_bf16_f32 v162, v158, v159
	v_cvt_pk_bf16_f32 v163, v160, v161
	v_cvt_pk_bf16_f32 v164, v154, v155
	v_cvt_pk_bf16_f32 v165, v156, v157
	s_waitcnt lgkmcnt(0)
	v_add_f32_e32 v146, v146, v147
	ds_bpermute_b32 v147, v139, v146
	global_store_dwordx4 v[166:167], v[162:165], off offset:256
	s_and_saveexec_b64 s[4:5], s[6:7]
	s_cbranch_execz .LBB0_1313
	s_waitcnt lgkmcnt(0)
	v_add_f32_e32 v154, v146, v147
	s_lshl_b32 s14, s10, 2
	v_lshlrev_b64 v[146:147], 8, v[144:145]
	s_ashr_i32 s15, s14, 31
	v_lshl_add_u64 v[146:147], s[18:19], 0, v[146:147]
	v_lshl_add_u64 v[146:147], s[14:15], 2, v[146:147]
	s_lshl_b32 s68, s65, 2
	v_lshl_add_u64 v[146:147], v[146:147], 0, s[68:69]
	global_store_dword v[146:147], v154, off
; __device__ __forceinline__ void store8bf(bf16_t* p, f32x4 a, f32x4 b) { u32x4 w; w.x = pk2(a[0], a[1]); w.y = pk2(a[2], a[3]); w.z = pk2(b[0], b[1]); w.w = pk2(b[2], b[3]); *(u32x4*)p = w; }
; __device__ __forceinline__ float sigmoid_f(float v) { return 1.0f / (1.0f + __expf(-v)); }
;     __device__ __forceinline__ void operator()(const f32x4 (&acc)[2][2][4][2], const pg8::Unit& u, int wr, int wc, int fr, int fq) const {
;     ...
;         const int rowb = u.pm * 256 + wr * 64 + fr, colb = u.pn * (GLU ? 128 : 256) + wc * 32 + 8 * fq;
; #pragma unroll
;         for (int ai = 0; ai < 2; ++ai)
; #pragma unroll
;             for (int m = 0; m < 4; ++m) {
;                 const int t = rowb + ai * 128 + m * 16; float ss = 0.f;
;                 float* xr = X + (size_t)t * D + colb; bf16_t* xbr = XB + (size_t)t * D + colb;
;                 if (GLU) {
;                     f32x4 y0, y1;
; #pragma unroll
;                     for (int jj = 0; jj < 4; ++jj) { y0[jj] = acc[ai][0][m][0][jj] * sigmoid_f(acc[ai][1][m][0][jj]); y1[jj] = acc[ai][0][m][1][jj] * sigmoid_f(acc[ai][1][m][1][jj]); }
;                     const f32x4 x0 = *(const f32x4*)xr + y0, x1 = *(const f32x4*)(xr + 4) + y1;
;                     if (!dry) { *(f32x4*)xr = x0; *(f32x4*)(xr + 4) = x1; store8bf(xbr, x0, x1); }
;                     ss += (x0[0] * x0[0] + x0[1] * x0[1]) + (x0[2] * x0[2] + x0[3] * x0[3]) + (x1[0] * x1[0] + x1[1] * x1[1]) + (x1[2] * x1[2] + x1[3] * x1[3]);
;                 } else {
; #pragma unroll
;                     for (int bj = 0; bj < 2; ++bj) {
;                         const f32x4 x0 = *(const f32x4*)(xr + bj * 128) + acc[ai][bj][m][0], x1 = *(const f32x4*)(xr + bj * 128 + 4) + acc[ai][bj][m][1];
;                         if (!dry) { *(f32x4*)(xr + bj * 128) = x0; *(f32x4*)(xr + bj * 128 + 4) = x1; store8bf(xbr + bj * 128, x0, x1); }
;                         ss += (x0[0] * x0[0] + x0[1] * x0[1]) + (x0[2] * x0[2] + x0[3] * x0[3]) + (x1[0] * x1[0] + x1[1] * x1[1]) + (x1[2] * x1[2] + x1[3] * x1[3]);
;                     }
;                 }
;                 ss += __shfl_xor(ss, 16); ss += __shfl_xor(ss, 32);
;                 if (fq == 0 && !dry) rsp_next[(size_t)t * 64 + u.pn * 4 + wc] = ss;
;             }
.LBB0_1313:
	s_or_b64 exec, exec, s[4:5]
	v_or_b32_e32 v146, 16, v144
	s_waitcnt lgkmcnt(0)
	v_ashrrev_i32_e32 v147, 31, v146
	v_lshlrev_b64 v[154:155], 13, v[146:147]
	v_lshl_add_u64 v[166:167], v[142:143], 0, v[154:155]
	v_lshlrev_b64 v[154:155], 12, v[146:147]
	v_lshl_add_u64 v[168:169], v[140:141], 0, v[154:155]
	s_waitcnt vmcnt(18)
	v_mov_b64_e32 v[154:155], v[186:187]
	v_mov_b64_e32 v[156:157], v[188:189]
	v_mov_b64_e32 v[158:159], v[196:197]
	v_mov_b64_e32 v[160:161], v[198:199]
	v_pk_add_f32 v[156:157], v[114:115], v[156:157]
	v_pk_add_f32 v[158:159], v[116:117], v[158:159]
	v_pk_add_f32 v[160:161], v[118:119], v[160:161]
	v_mul_f32_e32 v145, v159, v159
	v_pk_add_f32 v[154:155], v[112:113], v[154:155]
	global_store_dwordx4 v[166:167], v[158:161], off
	global_store_dwordx4 v[166:167], v[154:157], off offset:16
	s_mov_b32 s100, 0x100200
	v_lshl_add_u64 v[190:191], v[216:217], 0, s[100:101]
	global_load_dwordx4 v[186:189], v[190:191], off offset:16
	global_load_dwordx4 v[196:199], v[190:191], off
	v_cvt_pk_bf16_f32 v162, v158, v159
	v_fmac_f32_e32 v145, v158, v158
	v_mul_f32_e32 v158, v161, v161
	v_cvt_pk_bf16_f32 v164, v154, v155
	v_fmac_f32_e32 v158, v160, v160
	v_mul_f32_e32 v155, v155, v155
	v_cvt_pk_bf16_f32 v163, v160, v161
	v_cvt_pk_bf16_f32 v165, v156, v157
	v_add_f32_e32 v145, v145, v158
	v_fmac_f32_e32 v155, v154, v154
	v_mul_f32_e32 v154, v157, v157
	global_store_dwordx4 v[168:169], v[162:165], off
	v_add_f32_e32 v145, v145, v155
	v_fmac_f32_e32 v154, v156, v156
	v_add_f32_e32 v145, v154, v145
	s_waitcnt vmcnt(21)
	v_mov_b64_e32 v[154:155], v[200:201]
	v_mov_b64_e32 v[156:157], v[202:203]
	v_mov_b64_e32 v[158:159], v[204:205]
	v_mov_b64_e32 v[160:161], v[206:207]
	v_pk_add_f32 v[156:157], v[90:91], v[156:157]
	v_pk_add_f32 v[160:161], v[94:95], v[160:161]
	v_pk_add_f32 v[158:159], v[92:93], v[158:159]
	v_pk_add_f32 v[154:155], v[88:89], v[154:155]
	global_store_dwordx4 v[166:167], v[158:161], off offset:512
	global_store_dwordx4 v[166:167], v[154:157], off offset:528
	s_mov_b32 s100, 0x120000
	v_lshl_add_u64 v[190:191], v[216:217], 0, s[100:101]
	global_load_dwordx4 v[200:203], v[190:191], off offset:16
	global_load_dwordx4 v[204:207], v[190:191], off
	v_cvt_pk_bf16_f32 v162, v158, v159
	v_mul_f32_e32 v159, v159, v159
	v_fmac_f32_e32 v159, v158, v158
	v_mul_f32_e32 v158, v161, v161
	v_cvt_pk_bf16_f32 v164, v154, v155
	v_fmac_f32_e32 v158, v160, v160
	v_mul_f32_e32 v155, v155, v155
	v_add_f32_e32 v158, v159, v158
	v_fmac_f32_e32 v155, v154, v154
	v_add_f32_e32 v154, v158, v155
	v_mul_f32_e32 v155, v157, v157
	v_fmac_f32_e32 v155, v156, v156
	v_add_f32_e32 v154, v155, v154
	v_add_f32_e32 v145, v145, v154
	ds_bpermute_b32 v154, v153, v145
	v_cvt_pk_bf16_f32 v163, v160, v161
	v_cvt_pk_bf16_f32 v165, v156, v157
	global_store_dwordx4 v[168:169], v[162:165], off offset:256
	s_waitcnt lgkmcnt(0)
	v_add_f32_e32 v145, v145, v154
	ds_bpermute_b32 v154, v139, v145
	s_and_saveexec_b64 s[4:5], s[6:7]
	s_cbranch_execz .LBB0_1315
	s_lshl_b32 s14, s10, 2
	v_lshlrev_b64 v[146:147], 8, v[146:147]
	s_ashr_i32 s15, s14, 31
	v_lshl_add_u64 v[146:147], s[18:19], 0, v[146:147]
	v_lshl_add_u64 v[146:147], s[14:15], 2, v[146:147]
	s_lshl_b32 s68, s65, 2
	s_waitcnt lgkmcnt(0)
	v_add_f32_e32 v145, v145, v154
	v_lshl_add_u64 v[146:147], v[146:147], 0, s[68:69]
	global_store_dword v[146:147], v145, off
.LBB0_1315:
	s_or_b64 exec, exec, s[4:5]
	v_or_b32_e32 v146, 32, v144
	v_ashrrev_i32_e32 v147, 31, v146
	s_waitcnt lgkmcnt(0)
	v_lshlrev_b64 v[154:155], 13, v[146:147]
	v_lshl_add_u64 v[166:167], v[142:143], 0, v[154:155]
	v_lshlrev_b64 v[154:155], 12, v[146:147]
	v_lshl_add_u64 v[168:169], v[140:141], 0, v[154:155]
	s_waitcnt vmcnt(24)
	v_mov_b64_e32 v[154:155], v[208:209]
	v_mov_b64_e32 v[156:157], v[210:211]
	v_mov_b64_e32 v[158:159], v[212:213]
	v_mov_b64_e32 v[160:161], v[214:215]
	v_pk_add_f32 v[156:157], v[98:99], v[156:157]
	v_pk_add_f32 v[158:159], v[100:101], v[158:159]
	v_pk_add_f32 v[160:161], v[102:103], v[160:161]
	v_mul_f32_e32 v145, v159, v159
	v_pk_add_f32 v[154:155], v[96:97], v[154:155]
	global_store_dwordx4 v[166:167], v[158:161], off
	global_store_dwordx4 v[166:167], v[154:157], off offset:16
	s_mov_b32 s100, 0x120200
	v_lshl_add_u64 v[190:191], v[216:217], 0, s[100:101]
	global_load_dwordx4 v[208:211], v[190:191], off offset:16
	global_load_dwordx4 v[212:215], v[190:191], off
	v_cvt_pk_bf16_f32 v162, v158, v159
	v_fmac_f32_e32 v145, v158, v158
	v_mul_f32_e32 v158, v161, v161
	v_cvt_pk_bf16_f32 v164, v154, v155
	v_fmac_f32_e32 v158, v160, v160
	v_mul_f32_e32 v155, v155, v155
	v_cvt_pk_bf16_f32 v163, v160, v161
	v_cvt_pk_bf16_f32 v165, v156, v157
	v_add_f32_e32 v145, v145, v158
	v_fmac_f32_e32 v155, v154, v154
	v_mul_f32_e32 v154, v157, v157
	global_store_dwordx4 v[168:169], v[162:165], off
	v_add_f32_e32 v145, v145, v155
	v_fmac_f32_e32 v154, v156, v156
	v_add_f32_e32 v145, v154, v145
	s_waitcnt vmcnt(27)
	v_mov_b64_e32 v[154:155], v[224:225]
	v_mov_b64_e32 v[156:157], v[226:227]
	v_mov_b64_e32 v[158:159], v[236:237]
	v_mov_b64_e32 v[160:161], v[238:239]
	v_pk_add_f32 v[156:157], v[74:75], v[156:157]
	v_pk_add_f32 v[160:161], v[78:79], v[160:161]
	v_pk_add_f32 v[158:159], v[76:77], v[158:159]
	v_pk_add_f32 v[154:155], v[72:73], v[154:155]
	global_store_dwordx4 v[166:167], v[158:161], off offset:512
	global_store_dwordx4 v[166:167], v[154:157], off offset:528
	s_mov_b32 s100, 0x140000
	v_lshl_add_u64 v[190:191], v[216:217], 0, s[100:101]
	global_load_dwordx4 v[224:227], v[190:191], off offset:16
	global_load_dwordx4 v[236:239], v[190:191], off
	v_cvt_pk_bf16_f32 v162, v158, v159
	v_mul_f32_e32 v159, v159, v159
	v_fmac_f32_e32 v159, v158, v158
	v_mul_f32_e32 v158, v161, v161
	v_cvt_pk_bf16_f32 v164, v154, v155
	v_fmac_f32_e32 v158, v160, v160
	v_mul_f32_e32 v155, v155, v155
	v_add_f32_e32 v158, v159, v158
	v_fmac_f32_e32 v155, v154, v154
	v_add_f32_e32 v154, v158, v155
	v_mul_f32_e32 v155, v157, v157
	v_fmac_f32_e32 v155, v156, v156
	v_add_f32_e32 v154, v155, v154
	v_add_f32_e32 v145, v145, v154
	ds_bpermute_b32 v154, v153, v145
	v_cvt_pk_bf16_f32 v163, v160, v161
	v_cvt_pk_bf16_f32 v165, v156, v157
	global_store_dwordx4 v[168:169], v[162:165], off offset:256
	s_waitcnt lgkmcnt(0)
	v_add_f32_e32 v145, v145, v154
	ds_bpermute_b32 v154, v139, v145
	s_and_saveexec_b64 s[4:5], s[6:7]
	s_cbranch_execz .LBB0_1317
	s_lshl_b32 s14, s10, 2
	v_lshlrev_b64 v[146:147], 8, v[146:147]
	s_ashr_i32 s15, s14, 31
	v_lshl_add_u64 v[146:147], s[18:19], 0, v[146:147]
	v_lshl_add_u64 v[146:147], s[14:15], 2, v[146:147]
	s_lshl_b32 s68, s65, 2
	s_waitcnt lgkmcnt(0)
	v_add_f32_e32 v145, v145, v154
	v_lshl_add_u64 v[146:147], v[146:147], 0, s[68:69]
	global_store_dword v[146:147], v145, off
; __device__ __forceinline__ void store8bf(bf16_t* p, f32x4 a, f32x4 b) { u32x4 w; w.x = pk2(a[0], a[1]); w.y = pk2(a[2], a[3]); w.z = pk2(b[0], b[1]); w.w = pk2(b[2], b[3]); *(u32x4*)p = w; }
; __device__ __forceinline__ float sigmoid_f(float v) { return 1.0f / (1.0f + __expf(-v)); }
;     __device__ __forceinline__ void operator()(const f32x4 (&acc)[2][2][4][2], const pg8::Unit& u, int wr, int wc, int fr, int fq) const {
;     ...
;         const int rowb = u.pm * 256 + wr * 64 + fr, colb = u.pn * (GLU ? 128 : 256) + wc * 32 + 8 * fq;
; #pragma unroll
;         for (int ai = 0; ai < 2; ++ai)
; #pragma unroll
;             for (int m = 0; m < 4; ++m) {
;                 const int t = rowb + ai * 128 + m * 16; float ss = 0.f;
;                 float* xr = X + (size_t)t * D + colb; bf16_t* xbr = XB + (size_t)t * D + colb;
;                 if (GLU) {
;                     f32x4 y0, y1;
; #pragma unroll
;                     for (int jj = 0; jj < 4; ++jj) { y0[jj] = acc[ai][0][m][0][jj] * sigmoid_f(acc[ai][1][m][0][jj]); y1[jj] = acc[ai][0][m][1][jj] * sigmoid_f(acc[ai][1][m][1][jj]); }
;                     const f32x4 x0 = *(const f32x4*)xr + y0, x1 = *(const f32x4*)(xr + 4) + y1;
;                     if (!dry) { *(f32x4*)xr = x0; *(f32x4*)(xr + 4) = x1; store8bf(xbr, x0, x1); }
;                     ss += (x0[0] * x0[0] + x0[1] * x0[1]) + (x0[2] * x0[2] + x0[3] * x0[3]) + (x1[0] * x1[0] + x1[1] * x1[1]) + (x1[2] * x1[2] + x1[3] * x1[3]);
;                 } else {
; #pragma unroll
;                     for (int bj = 0; bj < 2; ++bj) {
;                         const f32x4 x0 = *(const f32x4*)(xr + bj * 128) + acc[ai][bj][m][0], x1 = *(const f32x4*)(xr + bj * 128 + 4) + acc[ai][bj][m][1];
;                         if (!dry) { *(f32x4*)(xr + bj * 128) = x0; *(f32x4*)(xr + bj * 128 + 4) = x1; store8bf(xbr + bj * 128, x0, x1); }
;                         ss += (x0[0] * x0[0] + x0[1] * x0[1]) + (x0[2] * x0[2] + x0[3] * x0[3]) + (x1[0] * x1[0] + x1[1] * x1[1]) + (x1[2] * x1[2] + x1[3] * x1[3]);
;                     }
;                 }
;                 ss += __shfl_xor(ss, 16); ss += __shfl_xor(ss, 32);
;                 if (fq == 0 && !dry) rsp_next[(size_t)t * 64 + u.pn * 4 + wc] = ss;
;             }
.LBB0_1317:
	s_or_b64 exec, exec, s[4:5]
	v_or_b32_e32 v146, 48, v144
	v_ashrrev_i32_e32 v147, 31, v146
	s_waitcnt lgkmcnt(0)
	v_lshlrev_b64 v[154:155], 13, v[146:147]
	v_lshl_add_u64 v[166:167], v[142:143], 0, v[154:155]
	v_lshlrev_b64 v[154:155], 12, v[146:147]
	v_lshl_add_u64 v[168:169], v[140:141], 0, v[154:155]
	s_waitcnt vmcnt(30)
	v_mov_b64_e32 v[154:155], v[240:241]
	v_mov_b64_e32 v[156:157], v[242:243]
	v_mov_b64_e32 v[158:159], v[244:245]
	v_mov_b64_e32 v[160:161], v[246:247]
	v_pk_add_f32 v[156:157], v[82:83], v[156:157]
	v_pk_add_f32 v[158:159], v[84:85], v[158:159]
	v_pk_add_f32 v[160:161], v[86:87], v[160:161]
	v_mul_f32_e32 v145, v159, v159
	v_pk_add_f32 v[154:155], v[80:81], v[154:155]
	global_store_dwordx4 v[166:167], v[158:161], off
	global_store_dwordx4 v[166:167], v[154:157], off offset:16
	s_mov_b32 s100, 0x140200
	v_lshl_add_u64 v[190:191], v[216:217], 0, s[100:101]
	global_load_dwordx4 v[240:243], v[190:191], off offset:16
	global_load_dwordx4 v[244:247], v[190:191], off
	v_cvt_pk_bf16_f32 v162, v158, v159
	v_fmac_f32_e32 v145, v158, v158
	v_mul_f32_e32 v158, v161, v161
	v_cvt_pk_bf16_f32 v164, v154, v155
	v_fmac_f32_e32 v158, v160, v160
	v_mul_f32_e32 v155, v155, v155
	v_cvt_pk_bf16_f32 v163, v160, v161
	v_cvt_pk_bf16_f32 v165, v156, v157
	v_add_f32_e32 v145, v145, v158
	v_fmac_f32_e32 v155, v154, v154
	v_mul_f32_e32 v154, v157, v157
	global_store_dwordx4 v[168:169], v[162:165], off
	v_add_f32_e32 v145, v145, v155
	v_fmac_f32_e32 v154, v156, v156
	v_add_f32_e32 v145, v154, v145
	s_waitcnt vmcnt(31)
	v_mov_b64_e32 v[154:155], v[170:171]
	v_mov_b64_e32 v[156:157], v[172:173]
	v_mov_b64_e32 v[158:159], v[174:175]
	v_mov_b64_e32 v[160:161], v[176:177]
	v_pk_add_f32 v[156:157], v[66:67], v[156:157]
	v_pk_add_f32 v[160:161], v[70:71], v[160:161]
	v_pk_add_f32 v[158:159], v[68:69], v[158:159]
	v_pk_add_f32 v[154:155], v[64:65], v[154:155]
	global_store_dwordx4 v[166:167], v[158:161], off offset:512
	global_store_dwordx4 v[166:167], v[154:157], off offset:528
	s_mov_b32 s100, 0x160000
	v_lshl_add_u64 v[190:191], v[216:217], 0, s[100:101]
	global_load_dwordx4 v[170:173], v[190:191], off offset:16
	global_load_dwordx4 v[174:177], v[190:191], off
	v_cvt_pk_bf16_f32 v162, v158, v159
	v_mul_f32_e32 v159, v159, v159
	v_fmac_f32_e32 v159, v158, v158
	v_mul_f32_e32 v158, v161, v161
	v_cvt_pk_bf16_f32 v164, v154, v155
	v_fmac_f32_e32 v158, v160, v160
	v_mul_f32_e32 v155, v155, v155
	v_add_f32_e32 v158, v159, v158
	v_fmac_f32_e32 v155, v154, v154
	v_add_f32_e32 v154, v158, v155
	v_mul_f32_e32 v155, v157, v157
	v_fmac_f32_e32 v155, v156, v156
	v_add_f32_e32 v154, v155, v154
	v_add_f32_e32 v145, v145, v154
	ds_bpermute_b32 v154, v153, v145
	v_cvt_pk_bf16_f32 v163, v160, v161
	v_cvt_pk_bf16_f32 v165, v156, v157
	global_store_dwordx4 v[168:169], v[162:165], off offset:256
	s_waitcnt lgkmcnt(0)
	v_add_f32_e32 v145, v145, v154
	ds_bpermute_b32 v154, v139, v145
	s_and_saveexec_b64 s[4:5], s[6:7]
	s_cbranch_execz .LBB0_1319
	s_lshl_b32 s14, s10, 2
	v_lshlrev_b64 v[146:147], 8, v[146:147]
	s_ashr_i32 s15, s14, 31
	v_lshl_add_u64 v[146:147], s[18:19], 0, v[146:147]
	v_lshl_add_u64 v[146:147], s[14:15], 2, v[146:147]
	s_lshl_b32 s68, s65, 2
	s_waitcnt lgkmcnt(0)
	v_add_f32_e32 v145, v145, v154
	v_lshl_add_u64 v[146:147], v[146:147], 0, s[68:69]
	global_store_dword v[146:147], v145, off
.LBB0_1319:
	s_or_b64 exec, exec, s[4:5]
	v_add_u32_e32 v146, 0x80, v144
	v_ashrrev_i32_e32 v147, 31, v146
	s_waitcnt lgkmcnt(0)
	v_lshlrev_b64 v[154:155], 13, v[146:147]
	v_lshl_add_u64 v[166:167], v[142:143], 0, v[154:155]
	v_lshlrev_b64 v[154:155], 12, v[146:147]
	v_lshl_add_u64 v[168:169], v[140:141], 0, v[154:155]
	s_waitcnt vmcnt(31)
	v_mov_b64_e32 v[154:155], v[178:179]
	v_mov_b64_e32 v[156:157], v[180:181]
	v_mov_b64_e32 v[158:159], v[182:183]
	v_mov_b64_e32 v[160:161], v[184:185]
	v_pk_add_f32 v[156:157], v[58:59], v[156:157]
	v_pk_add_f32 v[158:159], v[60:61], v[158:159]
	v_pk_add_f32 v[160:161], v[62:63], v[160:161]
	v_mul_f32_e32 v145, v159, v159
	v_pk_add_f32 v[154:155], v[56:57], v[154:155]
	global_store_dwordx4 v[166:167], v[158:161], off
	global_store_dwordx4 v[166:167], v[154:157], off offset:16
	s_mov_b32 s100, 0x160200
	v_lshl_add_u64 v[190:191], v[216:217], 0, s[100:101]
	global_load_dwordx4 v[178:181], v[190:191], off offset:16
	global_load_dwordx4 v[182:185], v[190:191], off
	v_cvt_pk_bf16_f32 v162, v158, v159
	v_fmac_f32_e32 v145, v158, v158
	v_mul_f32_e32 v158, v161, v161
	v_cvt_pk_bf16_f32 v164, v154, v155
	v_fmac_f32_e32 v158, v160, v160
	v_mul_f32_e32 v155, v155, v155
	v_cvt_pk_bf16_f32 v163, v160, v161
	v_cvt_pk_bf16_f32 v165, v156, v157
	v_add_f32_e32 v145, v145, v158
	v_fmac_f32_e32 v155, v154, v154
	v_mul_f32_e32 v154, v157, v157
	global_store_dwordx4 v[168:169], v[162:165], off
	v_add_f32_e32 v145, v145, v155
	v_fmac_f32_e32 v154, v156, v156
	v_add_f32_e32 v145, v154, v145
	s_waitcnt vmcnt(31)
	v_mov_b64_e32 v[154:155], v[186:187]
	v_mov_b64_e32 v[156:157], v[188:189]
	v_mov_b64_e32 v[158:159], v[196:197]
	v_mov_b64_e32 v[160:161], v[198:199]
	v_pk_add_f32 v[156:157], v[42:43], v[156:157]
	v_pk_add_f32 v[160:161], v[46:47], v[160:161]
	v_pk_add_f32 v[158:159], v[44:45], v[158:159]
	v_pk_add_f32 v[154:155], v[40:41], v[154:155]
	global_store_dwordx4 v[166:167], v[158:161], off offset:512
	global_store_dwordx4 v[166:167], v[154:157], off offset:528
	v_cvt_pk_bf16_f32 v162, v158, v159
	v_mul_f32_e32 v159, v159, v159
	v_fmac_f32_e32 v159, v158, v158
	v_mul_f32_e32 v158, v161, v161
	v_cvt_pk_bf16_f32 v164, v154, v155
	v_fmac_f32_e32 v158, v160, v160
	v_mul_f32_e32 v155, v155, v155
	v_add_f32_e32 v158, v159, v158
	v_fmac_f32_e32 v155, v154, v154
	v_add_f32_e32 v154, v158, v155
	v_mul_f32_e32 v155, v157, v157
	v_fmac_f32_e32 v155, v156, v156
	v_add_f32_e32 v154, v155, v154
	v_add_f32_e32 v145, v145, v154
	ds_bpermute_b32 v154, v153, v145
	v_cvt_pk_bf16_f32 v163, v160, v161
	v_cvt_pk_bf16_f32 v165, v156, v157
	global_store_dwordx4 v[168:169], v[162:165], off offset:256
	s_waitcnt lgkmcnt(0)
	v_add_f32_e32 v145, v145, v154
	ds_bpermute_b32 v154, v139, v145
	s_and_saveexec_b64 s[4:5], s[6:7]
	s_cbranch_execz .LBB0_1321
	s_lshl_b32 s14, s10, 2
	v_lshlrev_b64 v[146:147], 8, v[146:147]
	s_ashr_i32 s15, s14, 31
	v_lshl_add_u64 v[146:147], s[18:19], 0, v[146:147]
	v_lshl_add_u64 v[146:147], s[14:15], 2, v[146:147]
	s_lshl_b32 s68, s65, 2
	s_waitcnt lgkmcnt(0)
	v_add_f32_e32 v145, v145, v154
	v_lshl_add_u64 v[146:147], v[146:147], 0, s[68:69]
	global_store_dword v[146:147], v145, off
; __device__ __forceinline__ void store8bf(bf16_t* p, f32x4 a, f32x4 b) { u32x4 w; w.x = pk2(a[0], a[1]); w.y = pk2(a[2], a[3]); w.z = pk2(b[0], b[1]); w.w = pk2(b[2], b[3]); *(u32x4*)p = w; }
; __device__ __forceinline__ float sigmoid_f(float v) { return 1.0f / (1.0f + __expf(-v)); }
;     __device__ __forceinline__ void operator()(const f32x4 (&acc)[2][2][4][2], const pg8::Unit& u, int wr, int wc, int fr, int fq) const {
;     ...
;         const int rowb = u.pm * 256 + wr * 64 + fr, colb = u.pn * (GLU ? 128 : 256) + wc * 32 + 8 * fq;
; #pragma unroll
;         for (int ai = 0; ai < 2; ++ai)
; #pragma unroll
;             for (int m = 0; m < 4; ++m) {
;                 const int t = rowb + ai * 128 + m * 16; float ss = 0.f;
;                 float* xr = X + (size_t)t * D + colb; bf16_t* xbr = XB + (size_t)t * D + colb;
;                 if (GLU) {
;                     f32x4 y0, y1;
; #pragma unroll
;                     for (int jj = 0; jj < 4; ++jj) { y0[jj] = acc[ai][0][m][0][jj] * sigmoid_f(acc[ai][1][m][0][jj]); y1[jj] = acc[ai][0][m][1][jj] * sigmoid_f(acc[ai][1][m][1][jj]); }
;                     const f32x4 x0 = *(const f32x4*)xr + y0, x1 = *(const f32x4*)(xr + 4) + y1;
;                     if (!dry) { *(f32x4*)xr = x0; *(f32x4*)(xr + 4) = x1; store8bf(xbr, x0, x1); }
;                     ss += (x0[0] * x0[0] + x0[1] * x0[1]) + (x0[2] * x0[2] + x0[3] * x0[3]) + (x1[0] * x1[0] + x1[1] * x1[1]) + (x1[2] * x1[2] + x1[3] * x1[3]);
;                 } else {
; #pragma unroll
;                     for (int bj = 0; bj < 2; ++bj) {
;                         const f32x4 x0 = *(const f32x4*)(xr + bj * 128) + acc[ai][bj][m][0], x1 = *(const f32x4*)(xr + bj * 128 + 4) + acc[ai][bj][m][1];
;                         if (!dry) { *(f32x4*)(xr + bj * 128) = x0; *(f32x4*)(xr + bj * 128 + 4) = x1; store8bf(xbr + bj * 128, x0, x1); }
;                         ss += (x0[0] * x0[0] + x0[1] * x0[1]) + (x0[2] * x0[2] + x0[3] * x0[3]) + (x1[0] * x1[0] + x1[1] * x1[1]) + (x1[2] * x1[2] + x1[3] * x1[3]);
;                     }
;                 }
;                 ss += __shfl_xor(ss, 16); ss += __shfl_xor(ss, 32);
;                 if (fq == 0 && !dry) rsp_next[(size_t)t * 64 + u.pn * 4 + wc] = ss;
;             }
.LBB0_1321:
	s_or_b64 exec, exec, s[4:5]
	v_add_u32_e32 v146, 0x90, v144
	v_ashrrev_i32_e32 v147, 31, v146
	s_waitcnt lgkmcnt(0)
	v_lshlrev_b64 v[154:155], 13, v[146:147]
	v_lshl_add_u64 v[166:167], v[142:143], 0, v[154:155]
	v_lshlrev_b64 v[154:155], 12, v[146:147]
	v_lshl_add_u64 v[168:169], v[140:141], 0, v[154:155]
	s_waitcnt vmcnt(29)
	v_mov_b64_e32 v[154:155], v[200:201]
	v_mov_b64_e32 v[156:157], v[202:203]
	v_mov_b64_e32 v[158:159], v[204:205]
	v_mov_b64_e32 v[160:161], v[206:207]
	v_pk_add_f32 v[156:157], v[50:51], v[156:157]
	v_pk_add_f32 v[158:159], v[52:53], v[158:159]
	v_pk_add_f32 v[160:161], v[54:55], v[160:161]
	v_mul_f32_e32 v145, v159, v159
	v_pk_add_f32 v[154:155], v[48:49], v[154:155]
	global_store_dwordx4 v[166:167], v[158:161], off
	global_store_dwordx4 v[166:167], v[154:157], off offset:16
	v_cvt_pk_bf16_f32 v162, v158, v159
	v_fmac_f32_e32 v145, v158, v158
	v_mul_f32_e32 v158, v161, v161
	v_cvt_pk_bf16_f32 v164, v154, v155
	v_fmac_f32_e32 v158, v160, v160
	v_mul_f32_e32 v155, v155, v155
	v_cvt_pk_bf16_f32 v163, v160, v161
	v_cvt_pk_bf16_f32 v165, v156, v157
	v_add_f32_e32 v145, v145, v158
	v_fmac_f32_e32 v155, v154, v154
	v_mul_f32_e32 v154, v157, v157
	global_store_dwordx4 v[168:169], v[162:165], off
	v_add_f32_e32 v145, v145, v155
	v_fmac_f32_e32 v154, v156, v156
	v_add_f32_e32 v145, v154, v145
	s_waitcnt vmcnt(27)
	v_mov_b64_e32 v[154:155], v[208:209]
	v_mov_b64_e32 v[156:157], v[210:211]
	v_mov_b64_e32 v[158:159], v[212:213]
	v_mov_b64_e32 v[160:161], v[214:215]
	v_pk_add_f32 v[156:157], v[26:27], v[156:157]
	v_pk_add_f32 v[160:161], v[30:31], v[160:161]
	v_pk_add_f32 v[158:159], v[28:29], v[158:159]
	v_pk_add_f32 v[154:155], v[24:25], v[154:155]
	global_store_dwordx4 v[166:167], v[158:161], off offset:512
	global_store_dwordx4 v[166:167], v[154:157], off offset:528
	v_cvt_pk_bf16_f32 v162, v158, v159
	v_mul_f32_e32 v159, v159, v159
	v_fmac_f32_e32 v159, v158, v158
	v_mul_f32_e32 v158, v161, v161
	v_cvt_pk_bf16_f32 v164, v154, v155
	v_fmac_f32_e32 v158, v160, v160
	v_mul_f32_e32 v155, v155, v155
	v_add_f32_e32 v158, v159, v158
	v_fmac_f32_e32 v155, v154, v154
	v_add_f32_e32 v154, v158, v155
	v_mul_f32_e32 v155, v157, v157
	v_fmac_f32_e32 v155, v156, v156
	v_add_f32_e32 v154, v155, v154
	v_add_f32_e32 v145, v145, v154
	ds_bpermute_b32 v154, v153, v145
	v_cvt_pk_bf16_f32 v163, v160, v161
	v_cvt_pk_bf16_f32 v165, v156, v157
	global_store_dwordx4 v[168:169], v[162:165], off offset:256
	s_waitcnt lgkmcnt(0)
	v_add_f32_e32 v145, v145, v154
	ds_bpermute_b32 v154, v139, v145
	s_and_saveexec_b64 s[4:5], s[6:7]
	s_cbranch_execz .LBB0_1323
	s_lshl_b32 s14, s10, 2
	v_lshlrev_b64 v[146:147], 8, v[146:147]
	s_ashr_i32 s15, s14, 31
	v_lshl_add_u64 v[146:147], s[18:19], 0, v[146:147]
	v_lshl_add_u64 v[146:147], s[14:15], 2, v[146:147]
	s_lshl_b32 s68, s65, 2
	s_waitcnt lgkmcnt(0)
	v_add_f32_e32 v145, v145, v154
	v_lshl_add_u64 v[146:147], v[146:147], 0, s[68:69]
	global_store_dword v[146:147], v145, off
; __device__ __forceinline__ void store8bf(bf16_t* p, f32x4 a, f32x4 b) { u32x4 w; w.x = pk2(a[0], a[1]); w.y = pk2(a[2], a[3]); w.z = pk2(b[0], b[1]); w.w = pk2(b[2], b[3]); *(u32x4*)p = w; }
; __device__ __forceinline__ float sigmoid_f(float v) { return 1.0f / (1.0f + __expf(-v)); }
;     __device__ __forceinline__ void operator()(const f32x4 (&acc)[2][2][4][2], const pg8::Unit& u, int wr, int wc, int fr, int fq) const {
;     ...
;         const int rowb = u.pm * 256 + wr * 64 + fr, colb = u.pn * (GLU ? 128 : 256) + wc * 32 + 8 * fq;
; #pragma unroll
;         for (int ai = 0; ai < 2; ++ai)
; #pragma unroll
;             for (int m = 0; m < 4; ++m) {
;                 const int t = rowb + ai * 128 + m * 16; float ss = 0.f;
;                 float* xr = X + (size_t)t * D + colb; bf16_t* xbr = XB + (size_t)t * D + colb;
;                 if (GLU) {
;                     f32x4 y0, y1;
; #pragma unroll
;                     for (int jj = 0; jj < 4; ++jj) { y0[jj] = acc[ai][0][m][0][jj] * sigmoid_f(acc[ai][1][m][0][jj]); y1[jj] = acc[ai][0][m][1][jj] * sigmoid_f(acc[ai][1][m][1][jj]); }
;                     const f32x4 x0 = *(const f32x4*)xr + y0, x1 = *(const f32x4*)(xr + 4) + y1;
;                     if (!dry) { *(f32x4*)xr = x0; *(f32x4*)(xr + 4) = x1; store8bf(xbr, x0, x1); }
;                     ss += (x0[0] * x0[0] + x0[1] * x0[1]) + (x0[2] * x0[2] + x0[3] * x0[3]) + (x1[0] * x1[0] + x1[1] * x1[1]) + (x1[2] * x1[2] + x1[3] * x1[3]);
;                 } else {
; #pragma unroll
;                     for (int bj = 0; bj < 2; ++bj) {
;                         const f32x4 x0 = *(const f32x4*)(xr + bj * 128) + acc[ai][bj][m][0], x1 = *(const f32x4*)(xr + bj * 128 + 4) + acc[ai][bj][m][1];
;                         if (!dry) { *(f32x4*)(xr + bj * 128) = x0; *(f32x4*)(xr + bj * 128 + 4) = x1; store8bf(xbr + bj * 128, x0, x1); }
;                         ss += (x0[0] * x0[0] + x0[1] * x0[1]) + (x0[2] * x0[2] + x0[3] * x0[3]) + (x1[0] * x1[0] + x1[1] * x1[1]) + (x1[2] * x1[2] + x1[3] * x1[3]);
;                     }
;                 }
;                 ss += __shfl_xor(ss, 16); ss += __shfl_xor(ss, 32);
;                 if (fq == 0 && !dry) rsp_next[(size_t)t * 64 + u.pn * 4 + wc] = ss;
;             }
.LBB0_1323:
	s_or_b64 exec, exec, s[4:5]
	v_add_u32_e32 v146, 0xa0, v144
	v_ashrrev_i32_e32 v147, 31, v146
	s_waitcnt lgkmcnt(0)
	v_lshlrev_b64 v[154:155], 13, v[146:147]
	v_lshl_add_u64 v[166:167], v[142:143], 0, v[154:155]
	v_lshlrev_b64 v[154:155], 12, v[146:147]
	v_lshl_add_u64 v[168:169], v[140:141], 0, v[154:155]
	s_waitcnt vmcnt(25)
	v_mov_b64_e32 v[154:155], v[224:225]
	v_mov_b64_e32 v[156:157], v[226:227]
	v_mov_b64_e32 v[158:159], v[236:237]
	v_mov_b64_e32 v[160:161], v[238:239]
	v_pk_add_f32 v[156:157], v[34:35], v[156:157]
	v_pk_add_f32 v[158:159], v[36:37], v[158:159]
	v_pk_add_f32 v[160:161], v[38:39], v[160:161]
	v_mul_f32_e32 v145, v159, v159
	v_pk_add_f32 v[154:155], v[32:33], v[154:155]
	global_store_dwordx4 v[166:167], v[158:161], off
	global_store_dwordx4 v[166:167], v[154:157], off offset:16
	v_cvt_pk_bf16_f32 v162, v158, v159
	v_fmac_f32_e32 v145, v158, v158
	v_mul_f32_e32 v158, v161, v161
	v_cvt_pk_bf16_f32 v164, v154, v155
	v_fmac_f32_e32 v158, v160, v160
	v_mul_f32_e32 v155, v155, v155
	v_cvt_pk_bf16_f32 v163, v160, v161
	v_cvt_pk_bf16_f32 v165, v156, v157
	v_add_f32_e32 v145, v145, v158
	v_fmac_f32_e32 v155, v154, v154
	v_mul_f32_e32 v154, v157, v157
	global_store_dwordx4 v[168:169], v[162:165], off
	v_add_f32_e32 v145, v145, v155
	v_fmac_f32_e32 v154, v156, v156
	v_add_f32_e32 v145, v154, v145
	s_waitcnt vmcnt(23)
	v_mov_b64_e32 v[154:155], v[240:241]
	v_mov_b64_e32 v[156:157], v[242:243]
	v_mov_b64_e32 v[158:159], v[244:245]
	v_mov_b64_e32 v[160:161], v[246:247]
	v_pk_add_f32 v[156:157], v[10:11], v[156:157]
	v_pk_add_f32 v[160:161], v[14:15], v[160:161]
	v_pk_add_f32 v[158:159], v[12:13], v[158:159]
	v_pk_add_f32 v[154:155], v[8:9], v[154:155]
	global_store_dwordx4 v[166:167], v[158:161], off offset:512
	global_store_dwordx4 v[166:167], v[154:157], off offset:528
	v_cvt_pk_bf16_f32 v162, v158, v159
	v_mul_f32_e32 v159, v159, v159
	v_fmac_f32_e32 v159, v158, v158
	v_mul_f32_e32 v158, v161, v161
	v_cvt_pk_bf16_f32 v164, v154, v155
	v_fmac_f32_e32 v158, v160, v160
	v_mul_f32_e32 v155, v155, v155
	v_add_f32_e32 v158, v159, v158
	v_fmac_f32_e32 v155, v154, v154
	v_add_f32_e32 v154, v158, v155
	v_mul_f32_e32 v155, v157, v157
	v_fmac_f32_e32 v155, v156, v156
	v_add_f32_e32 v154, v155, v154
	v_add_f32_e32 v145, v145, v154
	ds_bpermute_b32 v154, v153, v145
	v_cvt_pk_bf16_f32 v163, v160, v161
	v_cvt_pk_bf16_f32 v165, v156, v157
	global_store_dwordx4 v[168:169], v[162:165], off offset:256
	s_waitcnt lgkmcnt(0)
	v_add_f32_e32 v145, v145, v154
	ds_bpermute_b32 v154, v139, v145
	s_and_saveexec_b64 s[4:5], s[6:7]
	s_cbranch_execz .LBB0_1325
	s_lshl_b32 s14, s10, 2
	v_lshlrev_b64 v[146:147], 8, v[146:147]
	s_ashr_i32 s15, s14, 31
	v_lshl_add_u64 v[146:147], s[18:19], 0, v[146:147]
	v_lshl_add_u64 v[146:147], s[14:15], 2, v[146:147]
	s_lshl_b32 s68, s65, 2
	s_waitcnt lgkmcnt(0)
	v_add_f32_e32 v145, v145, v154
	v_lshl_add_u64 v[146:147], v[146:147], 0, s[68:69]
	global_store_dword v[146:147], v145, off
.LBB0_1325:
	s_or_b64 exec, exec, s[4:5]
	v_add_u32_e32 v144, 0xb0, v144
	v_ashrrev_i32_e32 v145, 31, v144
	v_lshlrev_b64 v[146:147], 13, v[144:145]
	v_lshl_add_u64 v[146:147], v[142:143], 0, v[146:147]
	v_lshlrev_b64 v[142:143], 12, v[144:145]
	v_lshl_add_u64 v[162:163], v[140:141], 0, v[142:143]
	s_waitcnt vmcnt(21)
	v_mov_b64_e32 v[140:141], v[170:171]
	v_mov_b64_e32 v[142:143], v[172:173]
	v_mov_b64_e32 v[154:155], v[174:175]
	v_mov_b64_e32 v[156:157], v[176:177]
	s_waitcnt lgkmcnt(0)
	v_pk_add_f32 v[142:143], v[18:19], v[142:143]
	v_pk_add_f32 v[156:157], v[22:23], v[156:157]
	v_pk_add_f32 v[154:155], v[20:21], v[154:155]
	v_pk_add_f32 v[140:141], v[16:17], v[140:141]
	global_store_dwordx4 v[146:147], v[154:157], off
	global_store_dwordx4 v[146:147], v[140:143], off offset:16
	v_cvt_pk_bf16_f32 v158, v154, v155
	v_mul_f32_e32 v155, v155, v155
	v_fmac_f32_e32 v155, v154, v154
	v_mul_f32_e32 v154, v157, v157
	v_cvt_pk_bf16_f32 v160, v140, v141
	v_fmac_f32_e32 v154, v156, v156
	v_mul_f32_e32 v141, v141, v141
	v_add_f32_e32 v154, v155, v154
	v_fmac_f32_e32 v141, v140, v140
	v_cvt_pk_bf16_f32 v159, v156, v157
	v_cvt_pk_bf16_f32 v161, v142, v143
	v_add_f32_e32 v140, v154, v141
	v_mul_f32_e32 v141, v143, v143
	global_store_dwordx4 v[162:163], v[158:161], off
	v_fmac_f32_e32 v141, v142, v142
	v_add_f32_e32 v164, v141, v140
	s_waitcnt vmcnt(19)
	v_mov_b64_e32 v[140:141], v[178:179]
	v_mov_b64_e32 v[142:143], v[180:181]
	v_mov_b64_e32 v[154:155], v[182:183]
	v_mov_b64_e32 v[156:157], v[184:185]
	v_pk_add_f32 v[142:143], v[2:3], v[142:143]
	v_pk_add_f32 v[156:157], v[6:7], v[156:157]
	v_pk_add_f32 v[154:155], v[4:5], v[154:155]
	v_pk_add_f32 v[140:141], v[0:1], v[140:141]
	global_store_dwordx4 v[146:147], v[154:157], off offset:512
	global_store_dwordx4 v[146:147], v[140:143], off offset:528
	v_mul_f32_e32 v146, v155, v155
	v_mul_f32_e32 v147, v157, v157
	v_cvt_pk_bf16_f32 v160, v140, v141
	v_fmac_f32_e32 v146, v154, v154
	v_fmac_f32_e32 v147, v156, v156
	v_mul_f32_e32 v141, v141, v141
	v_add_f32_e32 v146, v146, v147
	v_fmac_f32_e32 v141, v140, v140
	v_add_f32_e32 v140, v146, v141
	v_mul_f32_e32 v141, v143, v143
	v_fmac_f32_e32 v141, v142, v142
	v_add_f32_e32 v140, v141, v140
	v_add_f32_e32 v140, v164, v140
	ds_bpermute_b32 v141, v153, v140
	v_cvt_pk_bf16_f32 v158, v154, v155
	v_cvt_pk_bf16_f32 v159, v156, v157
	v_cvt_pk_bf16_f32 v161, v142, v143
	global_store_dwordx4 v[162:163], v[158:161], off offset:256
	s_waitcnt lgkmcnt(0)
	v_add_f32_e32 v140, v140, v141
	ds_bpermute_b32 v139, v139, v140
	s_and_saveexec_b64 s[4:5], s[6:7]
	s_cbranch_execz .LBB0_1327
	s_waitcnt lgkmcnt(0)
	v_add_f32_e32 v139, v140, v139
	s_lshl_b32 s14, s10, 2
	v_lshlrev_b64 v[140:141], 8, v[144:145]
	s_ashr_i32 s15, s14, 31
	v_lshl_add_u64 v[140:141], s[18:19], 0, v[140:141]
	v_lshl_add_u64 v[140:141], s[14:15], 2, v[140:141]
	s_lshl_b32 s68, s65, 2
	v_lshl_add_u64 v[140:141], v[140:141], 0, s[68:69]
	global_store_dword v[140:141], v139, off
